# P0 weight-transpose tiles (4 of 6 matrices): both rounds of 16 row loads issued before the first wait (second register set) instead of two serialized load-wait rounds per tile
# speedup vs baseline: 1.0038x; 1.0038x over previous
; __device__ __forceinline__ void wave_lds_fence() { asm volatile("s_waitcnt lgkmcnt(0)" ::: "memory"); __builtin_amdgcn_wave_barrier(); }
; __device__ __forceinline__ void tr_tile(const float* W, int N, int k0, int n0, bf16_t* WT, int ldt, int drow0, float* scr, int lane) {
; #pragma unroll 8
;     for (int i = 0; i < 32; ++i) { const int kk = 2 * i + (lane >> 5); scr[kk * 33 + (lane & 31)] = W[(size_t)(k0 + kk) * N + n0 + (lane & 31)]; }
;     wave_lds_fence();
.LBB0_17:
	s_lshl_b32 s21, s11, 1
	s_lshl_b32 s36, s19, 1
	v_or_b32_e32 v27, s21, v1
	v_or_b32_e32 v33, s36, v2
	s_add_i32 s38, s21, 4
	s_add_i32 s39, s36, 4
	s_add_i32 s40, s21, 8
	s_add_i32 s41, s36, 8
	s_add_i32 s42, s21, 12
	s_add_i32 s43, s36, 12
	s_add_i32 s44, s21, 16
	s_add_i32 s45, s36, 16
	s_add_i32 s46, s21, 20
	s_add_i32 s47, s36, 20
	s_add_i32 s48, s21, 24
	s_add_i32 s49, s36, 24
	s_add_i32 s21, s21, 28
	s_add_i32 s36, s36, 28
	v_add_u32_e32 v36, s10, v33
	v_or_b32_e32 v64, s38, v1
	v_or_b32_e32 v68, s39, v2
	v_or_b32_e32 v69, s40, v1
	v_or_b32_e32 v70, s41, v2
	v_or_b32_e32 v71, s42, v1
	v_or_b32_e32 v72, s43, v2
	v_or_b32_e32 v73, s44, v1
	v_or_b32_e32 v74, s45, v2
	v_or_b32_e32 v75, s46, v1
	v_or_b32_e32 v76, s47, v2
	v_or_b32_e32 v77, s48, v1
	v_or_b32_e32 v78, s49, v2
	v_or_b32_e32 v79, s21, v1
	v_or_b32_e32 v80, s36, v2
	v_add_u32_e32 v34, s13, v27
	v_ashrrev_i32_e32 v37, 31, v36
	v_add_u32_e32 v38, s13, v64
	v_add_u32_e32 v40, s10, v68
	v_add_u32_e32 v42, s13, v69
	v_add_u32_e32 v44, s10, v70
	v_add_u32_e32 v46, s13, v71
	v_add_u32_e32 v48, s10, v72
	v_add_u32_e32 v50, s13, v73
	v_add_u32_e32 v52, s10, v74
	v_add_u32_e32 v54, s13, v75
	v_add_u32_e32 v56, s10, v76
	v_add_u32_e32 v58, s13, v77
	v_add_u32_e32 v60, s10, v78
	v_add_u32_e32 v62, s13, v79
	v_add_u32_e32 v66, s10, v80
	v_ashrrev_i32_e32 v35, 31, v34
	v_lshlrev_b64 v[36:37], 12, v[36:37]
	v_ashrrev_i32_e32 v41, 31, v40
	v_ashrrev_i32_e32 v39, 31, v38
	v_ashrrev_i32_e32 v45, 31, v44
	v_ashrrev_i32_e32 v43, 31, v42
	v_ashrrev_i32_e32 v49, 31, v48
	v_ashrrev_i32_e32 v47, 31, v46
	v_ashrrev_i32_e32 v53, 31, v52
	v_ashrrev_i32_e32 v51, 31, v50
	v_ashrrev_i32_e32 v57, 31, v56
	v_ashrrev_i32_e32 v55, 31, v54
	v_ashrrev_i32_e32 v61, 31, v60
	v_ashrrev_i32_e32 v59, 31, v58
	v_ashrrev_i32_e32 v67, 31, v66
	v_ashrrev_i32_e32 v63, 31, v62
	v_lshlrev_b64 v[34:35], 12, v[34:35]
	v_lshl_add_u64 v[36:37], v[28:29], 0, v[36:37]
	v_lshlrev_b64 v[38:39], 12, v[38:39]
	v_lshlrev_b64 v[40:41], 12, v[40:41]
	v_lshlrev_b64 v[42:43], 12, v[42:43]
	v_lshlrev_b64 v[44:45], 12, v[44:45]
	v_lshlrev_b64 v[46:47], 12, v[46:47]
	v_lshlrev_b64 v[48:49], 12, v[48:49]
	v_lshlrev_b64 v[50:51], 12, v[50:51]
	v_lshlrev_b64 v[52:53], 12, v[52:53]
	v_lshlrev_b64 v[54:55], 12, v[54:55]
	v_lshlrev_b64 v[56:57], 12, v[56:57]
	v_lshlrev_b64 v[58:59], 12, v[58:59]
	v_lshlrev_b64 v[60:61], 12, v[60:61]
	v_lshlrev_b64 v[62:63], 12, v[62:63]
	v_lshlrev_b64 v[66:67], 12, v[66:67]
	v_lshl_add_u64 v[34:35], v[28:29], 0, v[34:35]
	v_lshl_add_u64 v[40:41], v[28:29], 0, v[40:41]
	v_lshl_add_u64 v[38:39], v[28:29], 0, v[38:39]
	v_lshl_add_u64 v[44:45], v[28:29], 0, v[44:45]
	v_lshl_add_u64 v[42:43], v[28:29], 0, v[42:43]
	v_lshl_add_u64 v[48:49], v[28:29], 0, v[48:49]
	v_lshl_add_u64 v[46:47], v[28:29], 0, v[46:47]
	v_lshl_add_u64 v[52:53], v[28:29], 0, v[52:53]
	v_lshl_add_u64 v[50:51], v[28:29], 0, v[50:51]
	v_lshl_add_u64 v[56:57], v[28:29], 0, v[56:57]
	v_lshl_add_u64 v[54:55], v[28:29], 0, v[54:55]
	v_lshl_add_u64 v[60:61], v[28:29], 0, v[60:61]
	v_lshl_add_u64 v[58:59], v[28:29], 0, v[58:59]
	v_lshl_add_u64 v[66:67], v[28:29], 0, v[66:67]
	v_lshl_add_u64 v[62:63], v[28:29], 0, v[62:63]
	global_load_dword v81, v[36:37], off
	global_load_dword v82, v[34:35], off
	global_load_dword v83, v[40:41], off
	global_load_dword v84, v[38:39], off
	global_load_dword v85, v[44:45], off
	global_load_dword v86, v[42:43], off
	global_load_dword v87, v[48:49], off
	global_load_dword v88, v[46:47], off
	global_load_dword v89, v[52:53], off
	global_load_dword v90, v[50:51], off
	global_load_dword v91, v[56:57], off
	global_load_dword v92, v[54:55], off
	global_load_dword v93, v[60:61], off
	global_load_dword v94, v[58:59], off
	global_load_dword v95, v[66:67], off
	global_load_dword v96, v[62:63], off
	s_add_i32 s19, s19, 16
	s_add_i32 s11, s11, 16
	s_add_i32 s20, s20, -16
	v_mad_u64_u32 v[34:35], s[38:39], v33, s3, v[24:25]
	s_cmp_lg_u32 s20, 0
	v_mad_u64_u32 v[36:37], s[38:39], v27, s3, v[24:25]
	v_mad_u64_u32 v[38:39], s[38:39], v68, s3, v[24:25]
	v_mad_u64_u32 v[40:41], s[38:39], v64, s3, v[24:25]
	v_mad_u64_u32 v[42:43], s[38:39], v70, s3, v[24:25]
	v_mad_u64_u32 v[44:45], s[38:39], v69, s3, v[24:25]
	v_mad_u64_u32 v[46:47], s[38:39], v72, s3, v[24:25]
	v_mad_u64_u32 v[48:49], s[38:39], v71, s3, v[24:25]
	v_mad_u64_u32 v[50:51], s[38:39], v74, s3, v[24:25]
	v_mad_u64_u32 v[52:53], s[38:39], v73, s3, v[24:25]
	v_mad_u64_u32 v[54:55], s[38:39], v76, s3, v[24:25]
	v_mad_u64_u32 v[56:57], s[38:39], v75, s3, v[24:25]
	v_mad_u64_u32 v[58:59], s[38:39], v78, s3, v[24:25]
	v_mad_u64_u32 v[60:61], s[38:39], v77, s3, v[24:25]
	v_mad_u64_u32 v[62:63], s[38:39], v80, s3, v[24:25]
	v_mad_u64_u32 v[66:67], s[38:39], v79, s3, v[24:25]
	s_lshl_b32 s21, s11, 1
	s_lshl_b32 s36, s19, 1
	v_or_b32_e32 v183, s21, v1
	v_or_b32_e32 v117, s36, v2
	s_add_i32 s38, s21, 4
	s_add_i32 s39, s36, 4
	s_add_i32 s40, s21, 8
	s_add_i32 s41, s36, 8
	s_add_i32 s42, s21, 12
	s_add_i32 s43, s36, 12
	s_add_i32 s44, s21, 16
	s_add_i32 s45, s36, 16
	s_add_i32 s46, s21, 20
	s_add_i32 s47, s36, 20
	s_add_i32 s48, s21, 24
	s_add_i32 s49, s36, 24
	s_add_i32 s21, s21, 28
	s_add_i32 s36, s36, 28
	v_add_u32_e32 v120, s10, v117
	v_or_b32_e32 v148, s38, v1
	v_or_b32_e32 v152, s39, v2
	v_or_b32_e32 v153, s40, v1
	v_or_b32_e32 v154, s41, v2
	v_or_b32_e32 v155, s42, v1
	v_or_b32_e32 v156, s43, v2
	v_or_b32_e32 v157, s44, v1
	v_or_b32_e32 v158, s45, v2
	v_or_b32_e32 v159, s46, v1
	v_or_b32_e32 v160, s47, v2
	v_or_b32_e32 v161, s48, v1
	v_or_b32_e32 v162, s49, v2
	v_or_b32_e32 v163, s21, v1
	v_or_b32_e32 v164, s36, v2
	v_add_u32_e32 v118, s13, v183
	v_ashrrev_i32_e32 v121, 31, v120
; __device__ __forceinline__ void tr_tile(const float* W, int N, int k0, int n0, bf16_t* WT, int ldt, int drow0, float* scr, int lane) {
; #pragma unroll 8
;     for (int i = 0; i < 32; ++i) { const int kk = 2 * i + (lane >> 5); scr[kk * 33 + (lane & 31)] = W[(size_t)(k0 + kk) * N + n0 + (lane & 31)]; }
	v_add_u32_e32 v122, s13, v148
	v_add_u32_e32 v124, s10, v152
	v_add_u32_e32 v126, s13, v153
	v_add_u32_e32 v128, s10, v154
	v_add_u32_e32 v130, s13, v155
	v_add_u32_e32 v132, s10, v156
	v_add_u32_e32 v134, s13, v157
	v_add_u32_e32 v136, s10, v158
	v_add_u32_e32 v138, s13, v159
	v_add_u32_e32 v140, s10, v160
	v_add_u32_e32 v142, s13, v161
	v_add_u32_e32 v144, s10, v162
	v_add_u32_e32 v146, s13, v163
	v_add_u32_e32 v150, s10, v164
	v_ashrrev_i32_e32 v119, 31, v118
	v_lshlrev_b64 v[120:121], 12, v[120:121]
	v_ashrrev_i32_e32 v125, 31, v124
	v_ashrrev_i32_e32 v123, 31, v122
	v_ashrrev_i32_e32 v129, 31, v128
	v_ashrrev_i32_e32 v127, 31, v126
	v_ashrrev_i32_e32 v133, 31, v132
	v_ashrrev_i32_e32 v131, 31, v130
	v_ashrrev_i32_e32 v137, 31, v136
	v_ashrrev_i32_e32 v135, 31, v134
	v_ashrrev_i32_e32 v141, 31, v140
	v_ashrrev_i32_e32 v139, 31, v138
	v_ashrrev_i32_e32 v145, 31, v144
	v_ashrrev_i32_e32 v143, 31, v142
	v_ashrrev_i32_e32 v151, 31, v150
	v_ashrrev_i32_e32 v147, 31, v146
	v_lshlrev_b64 v[118:119], 12, v[118:119]
	v_lshl_add_u64 v[120:121], v[28:29], 0, v[120:121]
	v_lshlrev_b64 v[122:123], 12, v[122:123]
	v_lshlrev_b64 v[124:125], 12, v[124:125]
	v_lshlrev_b64 v[126:127], 12, v[126:127]
	v_lshlrev_b64 v[128:129], 12, v[128:129]
	v_lshlrev_b64 v[130:131], 12, v[130:131]
	v_lshlrev_b64 v[132:133], 12, v[132:133]
	v_lshlrev_b64 v[134:135], 12, v[134:135]
	v_lshlrev_b64 v[136:137], 12, v[136:137]
	v_lshlrev_b64 v[138:139], 12, v[138:139]
	v_lshlrev_b64 v[140:141], 12, v[140:141]
	v_lshlrev_b64 v[142:143], 12, v[142:143]
	v_lshlrev_b64 v[144:145], 12, v[144:145]
	v_lshlrev_b64 v[146:147], 12, v[146:147]
	v_lshlrev_b64 v[150:151], 12, v[150:151]
	v_lshl_add_u64 v[118:119], v[28:29], 0, v[118:119]
	v_lshl_add_u64 v[124:125], v[28:29], 0, v[124:125]
	v_lshl_add_u64 v[122:123], v[28:29], 0, v[122:123]
	v_lshl_add_u64 v[128:129], v[28:29], 0, v[128:129]
	v_lshl_add_u64 v[126:127], v[28:29], 0, v[126:127]
	v_lshl_add_u64 v[132:133], v[28:29], 0, v[132:133]
	v_lshl_add_u64 v[130:131], v[28:29], 0, v[130:131]
	v_lshl_add_u64 v[136:137], v[28:29], 0, v[136:137]
	v_lshl_add_u64 v[134:135], v[28:29], 0, v[134:135]
	v_lshl_add_u64 v[140:141], v[28:29], 0, v[140:141]
	v_lshl_add_u64 v[138:139], v[28:29], 0, v[138:139]
	v_lshl_add_u64 v[144:145], v[28:29], 0, v[144:145]
	v_lshl_add_u64 v[142:143], v[28:29], 0, v[142:143]
	v_lshl_add_u64 v[150:151], v[28:29], 0, v[150:151]
	v_lshl_add_u64 v[146:147], v[28:29], 0, v[146:147]
	global_load_dword v165, v[120:121], off
	global_load_dword v166, v[118:119], off
	global_load_dword v167, v[124:125], off
	global_load_dword v168, v[122:123], off
	global_load_dword v169, v[128:129], off
	global_load_dword v170, v[126:127], off
	global_load_dword v171, v[132:133], off
	global_load_dword v172, v[130:131], off
	global_load_dword v173, v[136:137], off
	global_load_dword v174, v[134:135], off
	global_load_dword v175, v[140:141], off
	global_load_dword v176, v[138:139], off
	global_load_dword v177, v[144:145], off
	global_load_dword v178, v[142:143], off
	global_load_dword v179, v[150:151], off
	global_load_dword v180, v[146:147], off
	s_add_i32 s19, s19, 16
	s_add_i32 s11, s11, 16
	s_add_i32 s20, s20, -16
	v_mad_u64_u32 v[118:119], s[38:39], v117, s3, v[24:25]
	s_cmp_lg_u32 s20, 0
	v_mad_u64_u32 v[120:121], s[38:39], v183, s3, v[24:25]
	v_mad_u64_u32 v[122:123], s[38:39], v152, s3, v[24:25]
	v_mad_u64_u32 v[124:125], s[38:39], v148, s3, v[24:25]
	v_mad_u64_u32 v[126:127], s[38:39], v154, s3, v[24:25]
	v_mad_u64_u32 v[128:129], s[38:39], v153, s3, v[24:25]
	v_mad_u64_u32 v[130:131], s[38:39], v156, s3, v[24:25]
	v_mad_u64_u32 v[132:133], s[38:39], v155, s3, v[24:25]
	v_mad_u64_u32 v[134:135], s[38:39], v158, s3, v[24:25]
	v_mad_u64_u32 v[136:137], s[38:39], v157, s3, v[24:25]
	v_mad_u64_u32 v[138:139], s[38:39], v160, s3, v[24:25]
	v_mad_u64_u32 v[140:141], s[38:39], v159, s3, v[24:25]
	v_mad_u64_u32 v[142:143], s[38:39], v162, s3, v[24:25]
	v_mad_u64_u32 v[144:145], s[38:39], v161, s3, v[24:25]
	v_mad_u64_u32 v[146:147], s[38:39], v164, s3, v[24:25]
	v_mad_u64_u32 v[150:151], s[38:39], v163, s3, v[24:25]
	s_waitcnt vmcnt(31)
	ds_write_b32 v34, v81
	s_waitcnt vmcnt(30)
	ds_write_b32 v36, v82
	s_waitcnt vmcnt(29)
	ds_write_b32 v38, v83
	s_waitcnt vmcnt(28)
	ds_write_b32 v40, v84
	s_waitcnt vmcnt(27)
	ds_write_b32 v42, v85
	s_waitcnt vmcnt(26)
	ds_write_b32 v44, v86
	s_waitcnt vmcnt(25)
	ds_write_b32 v46, v87
	s_waitcnt vmcnt(24)
	ds_write_b32 v48, v88
	s_waitcnt vmcnt(23)
	ds_write_b32 v50, v89
	s_waitcnt vmcnt(22)
	ds_write_b32 v52, v90
	s_waitcnt vmcnt(21)
	ds_write_b32 v54, v91
	s_waitcnt vmcnt(20)
	ds_write_b32 v56, v92
	s_waitcnt vmcnt(19)
	ds_write_b32 v58, v93
	s_waitcnt vmcnt(18)
	ds_write_b32 v60, v94
	s_waitcnt vmcnt(17)
	ds_write_b32 v62, v95
	s_waitcnt vmcnt(16)
	ds_write_b32 v66, v96
	s_waitcnt vmcnt(15)
	ds_write_b32 v118, v165
	s_waitcnt vmcnt(14)
	ds_write_b32 v120, v166
	s_waitcnt vmcnt(13)
	ds_write_b32 v122, v167
	s_waitcnt vmcnt(12)
	ds_write_b32 v124, v168
	s_waitcnt vmcnt(11)
	ds_write_b32 v126, v169
	s_waitcnt vmcnt(10)
	ds_write_b32 v128, v170
	s_waitcnt vmcnt(9)
	ds_write_b32 v130, v171
	s_waitcnt vmcnt(8)
	ds_write_b32 v132, v172
	s_waitcnt vmcnt(7)
	ds_write_b32 v134, v173
	s_waitcnt vmcnt(6)
	ds_write_b32 v136, v174
	s_waitcnt vmcnt(5)
	ds_write_b32 v138, v175
	s_waitcnt vmcnt(4)
	ds_write_b32 v140, v176
	s_waitcnt vmcnt(3)
	ds_write_b32 v142, v177
	s_waitcnt vmcnt(2)
	ds_write_b32 v144, v178
	s_waitcnt vmcnt(1)
	ds_write_b32 v146, v179
	s_waitcnt vmcnt(0)
	ds_write_b32 v150, v180
	s_cbranch_scc1 .LBB0_17
; __device__ __forceinline__ unsigned cvt_pk_bf16(float lo, float hi) { f32x2_t v = {lo, hi}; bf2_t r = __builtin_convertvector(v, bf2_t); return __builtin_bit_cast(unsigned, r); }
; __device__ __forceinline__ void wave_lds_fence() { asm volatile("s_waitcnt lgkmcnt(0)" ::: "memory"); __builtin_amdgcn_wave_barrier(); }
; __device__ __forceinline__ void tr_tile(const float* W, int N, int k0, int n0, bf16_t* WT, int ldt, int drow0, float* scr, int lane) {
;     ...
;     wave_lds_fence();
;     const int c = lane & 7;
; #pragma unroll
;     for (int j = 0; j < 4; ++j) { const int n = (lane >> 3) + 8 * j; const float* s = scr + (8 * c) * 33 + n;
;         u32x4 o; o.x = cvt_pk_bf16(s[0 * 33], s[1 * 33]); o.y = cvt_pk_bf16(s[2 * 33], s[3 * 33]); o.z = cvt_pk_bf16(s[4 * 33], s[5 * 33]); o.w = cvt_pk_bf16(s[6 * 33], s[7 * 33]);
;         *(u32x4*)(WT + (size_t)(drow0 + n) * ldt + k0 + 8 * c) = o; }
;     wave_lds_fence();
	s_waitcnt lgkmcnt(0)
	ds_read2_b32 v[28:29], v25 offset0:33 offset1:41
	ds_read2_b32 v[38:39], v25 offset1:8
	ds_read2_b32 v[40:41], v25 offset0:66 offset1:74
	ds_read2_b32 v[42:43], v25 offset0:99 offset1:107
	ds_read2_b32 v[44:45], v25 offset0:132 offset1:140
	ds_read2_b32 v[46:47], v25 offset0:165 offset1:173
	ds_read2_b32 v[48:49], v25 offset0:198 offset1:206
	ds_read2_b32 v[50:51], v25 offset0:231 offset1:239
	s_mov_b32 s11, s37
	v_or_b32_e32 v27, s12, v5
	v_lshl_add_u64 v[52:53], s[10:11], 1, v[8:9]
	v_mul_u32_u24_e32 v64, 0x1600, v27
	s_waitcnt lgkmcnt(6)
	v_cvt_pk_bf16_f32 v34, v38, v28
	s_waitcnt lgkmcnt(4)
	v_cvt_pk_bf16_f32 v35, v40, v42
	s_waitcnt lgkmcnt(2)
	v_cvt_pk_bf16_f32 v36, v44, v46
	s_waitcnt lgkmcnt(0)
	v_cvt_pk_bf16_f32 v37, v48, v50
	v_lshl_add_u64 v[54:55], v[52:53], 0, v[64:65]
	global_store_dwordx4 v[54:55], v[34:37], off
	v_or_b32_e32 v27, s12, v30
	v_mul_u32_u24_e32 v64, 0x1600, v27
	v_cvt_pk_bf16_f32 v34, v39, v29
	v_cvt_pk_bf16_f32 v35, v41, v43
	v_cvt_pk_bf16_f32 v36, v45, v47
	v_cvt_pk_bf16_f32 v37, v49, v51
	ds_read2_b32 v[38:39], v25 offset0:16 offset1:24
	ds_read2_b32 v[40:41], v25 offset0:49 offset1:57
	ds_read2_b32 v[42:43], v25 offset0:82 offset1:90
	ds_read2_b32 v[44:45], v25 offset0:115 offset1:123
	ds_read2_b32 v[46:47], v25 offset0:148 offset1:156
	ds_read2_b32 v[48:49], v25 offset0:181 offset1:189
	ds_read2_b32 v[50:51], v25 offset0:214 offset1:222
	ds_read2_b32 v[54:55], v25 offset0:247 offset1:255
	v_or_b32_e32 v27, s12, v31
	v_lshl_add_u64 v[28:29], v[52:53], 0, v[64:65]
	v_mul_u32_u24_e32 v64, 0x1600, v27
	v_or_b32_e32 v27, s12, v32
	global_store_dwordx4 v[28:29], v[34:37], off
	v_lshl_add_u64 v[28:29], v[52:53], 0, v[64:65]
	v_mul_u32_u24_e32 v64, 0x1600, v27
	s_waitcnt lgkmcnt(6)
	v_cvt_pk_bf16_f32 v34, v38, v40
	s_waitcnt lgkmcnt(4)
	v_cvt_pk_bf16_f32 v35, v42, v44
	s_waitcnt lgkmcnt(2)
	v_cvt_pk_bf16_f32 v36, v46, v48
	s_waitcnt lgkmcnt(0)
	v_cvt_pk_bf16_f32 v37, v50, v54
	global_store_dwordx4 v[28:29], v[34:37], off
	v_lshl_add_u64 v[28:29], v[52:53], 0, v[64:65]
	v_readlane_b32 s40, v254, 53
	v_cvt_pk_bf16_f32 v34, v39, v41
	v_cvt_pk_bf16_f32 v35, v43, v45
	v_cvt_pk_bf16_f32 v36, v47, v49
	v_cvt_pk_bf16_f32 v37, v51, v55
	global_store_dwordx4 v[28:29], v[34:37], off
	s_waitcnt lgkmcnt(0)
	s_mov_b64 s[10:11], 0
	v_readlane_b32 s41, v254, 54

; __device__ __forceinline__ void tr_tile(const float* W, int N, int k0, int n0, bf16_t* WT, int ldt, int drow0, float* scr, int lane) {
; #pragma unroll 8
;     for (int i = 0; i < 32; ++i) { const int kk = 2 * i + (lane >> 5); scr[kk * 33 + (lane & 31)] = W[(size_t)(k0 + kk) * N + n0 + (lane & 31)]; }
.LBB0_21:
	s_lshl_b32 s38, s19, 1
	s_lshl_b32 s39, s20, 1
	v_or_b32_e32 v27, s38, v1
	v_or_b32_e32 v33, s39, v2
	s_add_i32 s40, s38, 4
	s_add_i32 s41, s39, 4
	s_add_i32 s42, s38, 8
	s_add_i32 s43, s39, 8
	s_add_i32 s44, s38, 12
	s_add_i32 s45, s39, 12
	s_add_i32 s46, s38, 16
	s_add_i32 s47, s39, 16
	s_add_i32 s48, s38, 20
	s_add_i32 s49, s39, 20
	s_add_i32 s50, s38, 24
	s_add_i32 s51, s39, 24
	s_add_i32 s38, s38, 28
	s_add_i32 s39, s39, 28
	v_add_u32_e32 v34, s10, v33
	v_or_b32_e32 v64, s40, v1
	v_or_b32_e32 v68, s41, v2
	v_or_b32_e32 v69, s42, v1
	v_or_b32_e32 v70, s43, v2
	v_or_b32_e32 v71, s44, v1
	v_or_b32_e32 v72, s45, v2
	v_or_b32_e32 v73, s46, v1
	v_or_b32_e32 v74, s47, v2
	v_or_b32_e32 v75, s48, v1
	v_or_b32_e32 v76, s49, v2
	v_or_b32_e32 v77, s50, v1
	v_or_b32_e32 v78, s51, v2
	v_or_b32_e32 v79, s38, v1
	v_or_b32_e32 v80, s39, v2
	v_add_u32_e32 v36, s13, v27
	v_mad_u64_u32 v[34:35], s[38:39], v34, s22, v[28:29]
	v_add_u32_e32 v40, s13, v64
	v_add_u32_e32 v38, s10, v68
	v_add_u32_e32 v44, s13, v69
	v_add_u32_e32 v42, s10, v70
	v_add_u32_e32 v48, s13, v71
	v_add_u32_e32 v46, s10, v72
	v_add_u32_e32 v52, s13, v73
	v_add_u32_e32 v50, s10, v74
	v_add_u32_e32 v56, s13, v75
	v_add_u32_e32 v54, s10, v76
	v_add_u32_e32 v60, s13, v77
	v_add_u32_e32 v58, s10, v78
	v_add_u32_e32 v66, s13, v79
	v_add_u32_e32 v62, s10, v80
	v_mad_u64_u32 v[36:37], s[38:39], v36, s22, v[28:29]
	v_mad_u64_u32 v[38:39], s[38:39], v38, s22, v[28:29]
	v_mad_u64_u32 v[40:41], s[38:39], v40, s22, v[28:29]
	v_mad_u64_u32 v[42:43], s[38:39], v42, s22, v[28:29]
	v_mad_u64_u32 v[44:45], s[38:39], v44, s22, v[28:29]
	v_mad_u64_u32 v[46:47], s[38:39], v46, s22, v[28:29]
	v_mad_u64_u32 v[48:49], s[38:39], v48, s22, v[28:29]
	v_mad_u64_u32 v[50:51], s[38:39], v50, s22, v[28:29]
	v_mad_u64_u32 v[52:53], s[38:39], v52, s22, v[28:29]
	v_mad_u64_u32 v[54:55], s[38:39], v54, s22, v[28:29]
	v_mad_u64_u32 v[56:57], s[38:39], v56, s22, v[28:29]
	v_mad_u64_u32 v[58:59], s[38:39], v58, s22, v[28:29]
	v_mad_u64_u32 v[60:61], s[38:39], v60, s22, v[28:29]
	v_mad_u64_u32 v[62:63], s[38:39], v62, s22, v[28:29]
	v_mad_u64_u32 v[66:67], s[38:39], v66, s22, v[28:29]
	global_load_dword v81, v[34:35], off
	global_load_dword v82, v[36:37], off
	global_load_dword v83, v[38:39], off
	global_load_dword v84, v[40:41], off
	global_load_dword v85, v[42:43], off
	global_load_dword v86, v[44:45], off
	global_load_dword v87, v[46:47], off
	global_load_dword v88, v[48:49], off
	global_load_dword v89, v[50:51], off
	global_load_dword v90, v[52:53], off
	global_load_dword v91, v[54:55], off
	global_load_dword v92, v[56:57], off
	global_load_dword v93, v[58:59], off
	global_load_dword v94, v[60:61], off
	global_load_dword v95, v[62:63], off
	global_load_dword v96, v[66:67], off
	s_add_i32 s20, s20, 16
	s_add_i32 s19, s19, 16
	s_add_i32 s21, s21, -16
	v_mad_u64_u32 v[34:35], s[38:39], v33, s3, v[24:25]
	s_cmp_lg_u32 s21, 0
	v_mad_u64_u32 v[36:37], s[38:39], v27, s3, v[24:25]
	v_mad_u64_u32 v[38:39], s[38:39], v68, s3, v[24:25]
	v_mad_u64_u32 v[40:41], s[38:39], v64, s3, v[24:25]
	v_mad_u64_u32 v[42:43], s[38:39], v70, s3, v[24:25]
	v_mad_u64_u32 v[44:45], s[38:39], v69, s3, v[24:25]
	v_mad_u64_u32 v[46:47], s[38:39], v72, s3, v[24:25]
	v_mad_u64_u32 v[48:49], s[38:39], v71, s3, v[24:25]
	v_mad_u64_u32 v[50:51], s[38:39], v74, s3, v[24:25]
	v_mad_u64_u32 v[52:53], s[38:39], v73, s3, v[24:25]
	v_mad_u64_u32 v[54:55], s[38:39], v76, s3, v[24:25]
	v_mad_u64_u32 v[56:57], s[38:39], v75, s3, v[24:25]
	v_mad_u64_u32 v[58:59], s[38:39], v78, s3, v[24:25]
	v_mad_u64_u32 v[60:61], s[38:39], v77, s3, v[24:25]
	v_mad_u64_u32 v[62:63], s[38:39], v80, s3, v[24:25]
	v_mad_u64_u32 v[66:67], s[38:39], v79, s3, v[24:25]
	s_lshl_b32 s38, s19, 1
	s_lshl_b32 s39, s20, 1
	v_or_b32_e32 v183, s38, v1
	v_or_b32_e32 v117, s39, v2
	s_add_i32 s40, s38, 4
	s_add_i32 s41, s39, 4
	s_add_i32 s42, s38, 8
	s_add_i32 s43, s39, 8
	s_add_i32 s44, s38, 12
	s_add_i32 s45, s39, 12
	s_add_i32 s46, s38, 16
	s_add_i32 s47, s39, 16
	s_add_i32 s48, s38, 20
	s_add_i32 s49, s39, 20
	s_add_i32 s50, s38, 24
	s_add_i32 s51, s39, 24
	s_add_i32 s38, s38, 28
	s_add_i32 s39, s39, 28
	v_add_u32_e32 v118, s10, v117
	v_or_b32_e32 v148, s40, v1
	v_or_b32_e32 v152, s41, v2
	v_or_b32_e32 v153, s42, v1
	v_or_b32_e32 v154, s43, v2
	v_or_b32_e32 v155, s44, v1
	v_or_b32_e32 v156, s45, v2
	v_or_b32_e32 v157, s46, v1
	v_or_b32_e32 v158, s47, v2
	v_or_b32_e32 v159, s48, v1
	v_or_b32_e32 v160, s49, v2
	v_or_b32_e32 v161, s50, v1
	v_or_b32_e32 v162, s51, v2
	v_or_b32_e32 v163, s38, v1
	v_or_b32_e32 v164, s39, v2
	v_add_u32_e32 v120, s13, v183
	v_mad_u64_u32 v[118:119], s[38:39], v118, s22, v[28:29]
	v_add_u32_e32 v124, s13, v148
	v_add_u32_e32 v122, s10, v152
	v_add_u32_e32 v128, s13, v153
	v_add_u32_e32 v126, s10, v154
	v_add_u32_e32 v132, s13, v155
	v_add_u32_e32 v130, s10, v156
	v_add_u32_e32 v136, s13, v157
	v_add_u32_e32 v134, s10, v158
	v_add_u32_e32 v140, s13, v159
	v_add_u32_e32 v138, s10, v160
	v_add_u32_e32 v144, s13, v161
	v_add_u32_e32 v142, s10, v162
	v_add_u32_e32 v150, s13, v163
	v_add_u32_e32 v146, s10, v164
	v_mad_u64_u32 v[120:121], s[38:39], v120, s22, v[28:29]
	v_mad_u64_u32 v[122:123], s[38:39], v122, s22, v[28:29]
	v_mad_u64_u32 v[124:125], s[38:39], v124, s22, v[28:29]
	v_mad_u64_u32 v[126:127], s[38:39], v126, s22, v[28:29]
	v_mad_u64_u32 v[128:129], s[38:39], v128, s22, v[28:29]
	v_mad_u64_u32 v[130:131], s[38:39], v130, s22, v[28:29]
	v_mad_u64_u32 v[132:133], s[38:39], v132, s22, v[28:29]
	v_mad_u64_u32 v[134:135], s[38:39], v134, s22, v[28:29]
	v_mad_u64_u32 v[136:137], s[38:39], v136, s22, v[28:29]
	v_mad_u64_u32 v[138:139], s[38:39], v138, s22, v[28:29]
; __device__ __forceinline__ unsigned cvt_pk_bf16(float lo, float hi) { f32x2_t v = {lo, hi}; bf2_t r = __builtin_convertvector(v, bf2_t); return __builtin_bit_cast(unsigned, r); }
; __device__ __forceinline__ void wave_lds_fence() { asm volatile("s_waitcnt lgkmcnt(0)" ::: "memory"); __builtin_amdgcn_wave_barrier(); }
; __device__ __forceinline__ void tr_tile(const float* W, int N, int k0, int n0, bf16_t* WT, int ldt, int drow0, float* scr, int lane) {
;     ...
;     for (int i = 0; i < 32; ++i) { const int kk = 2 * i + (lane >> 5); scr[kk * 33 + (lane & 31)] = W[(size_t)(k0 + kk) * N + n0 + (lane & 31)]; }
;     wave_lds_fence();
;     const int c = lane & 7;
; #pragma unroll
;     for (int j = 0; j < 4; ++j) { const int n = (lane >> 3) + 8 * j; const float* s = scr + (8 * c) * 33 + n;
;         u32x4 o; o.x = cvt_pk_bf16(s[0 * 33], s[1 * 33]); o.y = cvt_pk_bf16(s[2 * 33], s[3 * 33]); o.z = cvt_pk_bf16(s[4 * 33], s[5 * 33]); o.w = cvt_pk_bf16(s[6 * 33], s[7 * 33]);
;         *(u32x4*)(WT + (size_t)(drow0 + n) * ldt + k0 + 8 * c) = o; }
	v_mad_u64_u32 v[140:141], s[38:39], v140, s22, v[28:29]
	v_mad_u64_u32 v[142:143], s[38:39], v142, s22, v[28:29]
	v_mad_u64_u32 v[144:145], s[38:39], v144, s22, v[28:29]
	v_mad_u64_u32 v[146:147], s[38:39], v146, s22, v[28:29]
	v_mad_u64_u32 v[150:151], s[38:39], v150, s22, v[28:29]
	global_load_dword v165, v[118:119], off
	global_load_dword v166, v[120:121], off
	global_load_dword v167, v[122:123], off
	global_load_dword v168, v[124:125], off
	global_load_dword v169, v[126:127], off
	global_load_dword v170, v[128:129], off
	global_load_dword v171, v[130:131], off
	global_load_dword v172, v[132:133], off
	global_load_dword v173, v[134:135], off
	global_load_dword v174, v[136:137], off
	global_load_dword v175, v[138:139], off
	global_load_dword v176, v[140:141], off
	global_load_dword v177, v[142:143], off
	global_load_dword v178, v[144:145], off
	global_load_dword v179, v[146:147], off
	global_load_dword v180, v[150:151], off
	s_add_i32 s20, s20, 16
	s_add_i32 s19, s19, 16
	s_add_i32 s21, s21, -16
	v_mad_u64_u32 v[118:119], s[38:39], v117, s3, v[24:25]
	s_cmp_lg_u32 s21, 0
	v_mad_u64_u32 v[120:121], s[38:39], v183, s3, v[24:25]
	v_mad_u64_u32 v[122:123], s[38:39], v152, s3, v[24:25]
	v_mad_u64_u32 v[124:125], s[38:39], v148, s3, v[24:25]
	v_mad_u64_u32 v[126:127], s[38:39], v154, s3, v[24:25]
	v_mad_u64_u32 v[128:129], s[38:39], v153, s3, v[24:25]
	v_mad_u64_u32 v[130:131], s[38:39], v156, s3, v[24:25]
	v_mad_u64_u32 v[132:133], s[38:39], v155, s3, v[24:25]
	v_mad_u64_u32 v[134:135], s[38:39], v158, s3, v[24:25]
	v_mad_u64_u32 v[136:137], s[38:39], v157, s3, v[24:25]
	v_mad_u64_u32 v[138:139], s[38:39], v160, s3, v[24:25]
	v_mad_u64_u32 v[140:141], s[38:39], v159, s3, v[24:25]
	v_mad_u64_u32 v[142:143], s[38:39], v162, s3, v[24:25]
	v_mad_u64_u32 v[144:145], s[38:39], v161, s3, v[24:25]
	v_mad_u64_u32 v[146:147], s[38:39], v164, s3, v[24:25]
	v_mad_u64_u32 v[150:151], s[38:39], v163, s3, v[24:25]
	s_waitcnt vmcnt(31)
	ds_write_b32 v34, v81
	s_waitcnt vmcnt(30)
	ds_write_b32 v36, v82
	s_waitcnt vmcnt(29)
	ds_write_b32 v38, v83
	s_waitcnt vmcnt(28)
	ds_write_b32 v40, v84
	s_waitcnt vmcnt(27)
	ds_write_b32 v42, v85
	s_waitcnt vmcnt(26)
	ds_write_b32 v44, v86
	s_waitcnt vmcnt(25)
	ds_write_b32 v46, v87
	s_waitcnt vmcnt(24)
	ds_write_b32 v48, v88
	s_waitcnt vmcnt(23)
	ds_write_b32 v50, v89
	s_waitcnt vmcnt(22)
	ds_write_b32 v52, v90
	s_waitcnt vmcnt(21)
	ds_write_b32 v54, v91
	s_waitcnt vmcnt(20)
	ds_write_b32 v56, v92
	s_waitcnt vmcnt(19)
	ds_write_b32 v58, v93
	s_waitcnt vmcnt(18)
	ds_write_b32 v60, v94
	s_waitcnt vmcnt(17)
	ds_write_b32 v62, v95
	s_waitcnt vmcnt(16)
	ds_write_b32 v66, v96
	s_waitcnt vmcnt(15)
	ds_write_b32 v118, v165
	s_waitcnt vmcnt(14)
	ds_write_b32 v120, v166
	s_waitcnt vmcnt(13)
	ds_write_b32 v122, v167
	s_waitcnt vmcnt(12)
	ds_write_b32 v124, v168
	s_waitcnt vmcnt(11)
	ds_write_b32 v126, v169
	s_waitcnt vmcnt(10)
	ds_write_b32 v128, v170
	s_waitcnt vmcnt(9)
	ds_write_b32 v130, v171
	s_waitcnt vmcnt(8)
	ds_write_b32 v132, v172
	s_waitcnt vmcnt(7)
	ds_write_b32 v134, v173
	s_waitcnt vmcnt(6)
	ds_write_b32 v136, v174
	s_waitcnt vmcnt(5)
	ds_write_b32 v138, v175
	s_waitcnt vmcnt(4)
	ds_write_b32 v140, v176
	s_waitcnt vmcnt(3)
	ds_write_b32 v142, v177
	s_waitcnt vmcnt(2)
	ds_write_b32 v144, v178
	s_waitcnt vmcnt(1)
	ds_write_b32 v146, v179
	s_waitcnt vmcnt(0)
	ds_write_b32 v150, v180
	s_cbranch_scc1 .LBB0_21
	s_lshl_b32 s12, s12, 6
	s_cmpk_gt_u32 s11, 0x57f
	s_cselect_b32 s11, 0x80, 0
	s_and_b32 s13, s36, 0x60
	s_waitcnt lgkmcnt(0)
	ds_read2_b32 v[28:29], v25 offset0:33 offset1:41
	ds_read2_b32 v[38:39], v25 offset1:8
	ds_read2_b32 v[40:41], v25 offset0:66 offset1:74
	ds_read2_b32 v[42:43], v25 offset0:99 offset1:107
	ds_read2_b32 v[44:45], v25 offset0:132 offset1:140
	ds_read2_b32 v[46:47], v25 offset0:165 offset1:173
	ds_read2_b32 v[48:49], v25 offset0:198 offset1:206
	ds_read2_b32 v[50:51], v25 offset0:231 offset1:239
	s_or_b32 s11, s13, s11
	s_and_b32 s12, s12, 0x1f00
	s_or_b32 s12, s11, s12
	s_mov_b32 s11, s37
	v_or_b32_e32 v27, s12, v5
	v_lshl_add_u64 v[52:53], s[10:11], 1, v[10:11]
	v_lshlrev_b32_e32 v64, 11, v27
	s_waitcnt lgkmcnt(6)
	v_cvt_pk_bf16_f32 v34, v38, v28
	s_waitcnt lgkmcnt(4)
	v_cvt_pk_bf16_f32 v35, v40, v42
	s_waitcnt lgkmcnt(2)
	v_cvt_pk_bf16_f32 v36, v44, v46
	s_waitcnt lgkmcnt(0)
	v_cvt_pk_bf16_f32 v37, v48, v50
	v_lshl_add_u64 v[54:55], v[52:53], 0, v[64:65]
	global_store_dwordx4 v[54:55], v[34:37], off
	v_or_b32_e32 v27, s12, v30
	v_lshlrev_b32_e32 v64, 11, v27
	v_cvt_pk_bf16_f32 v34, v39, v29
	v_cvt_pk_bf16_f32 v35, v41, v43
	v_cvt_pk_bf16_f32 v36, v45, v47
	v_cvt_pk_bf16_f32 v37, v49, v51
	ds_read2_b32 v[38:39], v25 offset0:49 offset1:57
	ds_read2_b32 v[40:41], v25 offset0:16 offset1:24
	ds_read2_b32 v[42:43], v25 offset0:82 offset1:90
	ds_read2_b32 v[44:45], v25 offset0:115 offset1:123
	ds_read2_b32 v[46:47], v25 offset0:148 offset1:156
	ds_read2_b32 v[48:49], v25 offset0:181 offset1:189
	ds_read2_b32 v[50:51], v25 offset0:214 offset1:222
	ds_read2_b32 v[54:55], v25 offset0:247 offset1:255
	v_or_b32_e32 v27, s12, v31
	v_lshl_add_u64 v[28:29], v[52:53], 0, v[64:65]
	v_lshlrev_b32_e32 v64, 11, v27
	v_or_b32_e32 v27, s12, v32
	global_store_dwordx4 v[28:29], v[34:37], off
	v_lshl_add_u64 v[28:29], v[52:53], 0, v[64:65]
	v_lshlrev_b32_e32 v64, 11, v27
	s_waitcnt lgkmcnt(6)
	v_cvt_pk_bf16_f32 v34, v40, v38
	s_waitcnt lgkmcnt(4)
	v_cvt_pk_bf16_f32 v35, v42, v44
	s_waitcnt lgkmcnt(2)
	v_cvt_pk_bf16_f32 v36, v46, v48
	s_waitcnt lgkmcnt(0)
	v_cvt_pk_bf16_f32 v37, v50, v54
	global_store_dwordx4 v[28:29], v[34:37], off
	v_lshl_add_u64 v[28:29], v[52:53], 0, v[64:65]
	v_readlane_b32 s40, v254, 53
	v_cvt_pk_bf16_f32 v34, v41, v39
	v_cvt_pk_bf16_f32 v35, v43, v45
	v_cvt_pk_bf16_f32 v36, v47, v49
	v_cvt_pk_bf16_f32 v37, v51, v55
	global_store_dwordx4 v[28:29], v[34:37], off
	s_waitcnt lgkmcnt(0)
	v_readlane_b32 s41, v254, 54

; __device__ __forceinline__ void wave_lds_fence() { asm volatile("s_waitcnt lgkmcnt(0)" ::: "memory"); __builtin_amdgcn_wave_barrier(); }
; __device__ __forceinline__ void tr_tile(const float* W, int N, int k0, int n0, bf16_t* WT, int ldt, int drow0, float* scr, int lane) {
; #pragma unroll 8
;     for (int i = 0; i < 32; ++i) { const int kk = 2 * i + (lane >> 5); scr[kk * 33 + (lane & 31)] = W[(size_t)(k0 + kk) * N + n0 + (lane & 31)]; }
;     wave_lds_fence();
.LBB0_26:
	s_lshl_b32 s21, s11, 1
	s_lshl_b32 s36, s19, 1
	v_or_b32_e32 v27, s21, v1
	v_or_b32_e32 v33, s36, v2
	s_add_i32 s38, s21, 4
	s_add_i32 s39, s36, 4
	s_add_i32 s40, s21, 8
	s_add_i32 s41, s36, 8
	s_add_i32 s42, s21, 12
	s_add_i32 s43, s36, 12
	s_add_i32 s44, s21, 16
	s_add_i32 s45, s36, 16
	s_add_i32 s46, s21, 20
	s_add_i32 s47, s36, 20
	s_add_i32 s48, s21, 24
	s_add_i32 s49, s36, 24
	s_add_i32 s21, s21, 28
	s_add_i32 s36, s36, 28
	v_add_u32_e32 v36, s10, v33
	v_or_b32_e32 v64, s38, v1
	v_or_b32_e32 v68, s39, v2
	v_or_b32_e32 v69, s40, v1
	v_or_b32_e32 v70, s41, v2
	v_or_b32_e32 v71, s42, v1
	v_or_b32_e32 v72, s43, v2
	v_or_b32_e32 v73, s44, v1
	v_or_b32_e32 v74, s45, v2
	v_or_b32_e32 v75, s46, v1
	v_or_b32_e32 v76, s47, v2
	v_or_b32_e32 v77, s48, v1
	v_or_b32_e32 v78, s49, v2
	v_or_b32_e32 v79, s21, v1
	v_or_b32_e32 v80, s36, v2
	v_add_u32_e32 v34, s13, v27
	v_ashrrev_i32_e32 v37, 31, v36
	v_add_u32_e32 v38, s13, v64
	v_add_u32_e32 v40, s10, v68
	v_add_u32_e32 v42, s13, v69
	v_add_u32_e32 v44, s10, v70
	v_add_u32_e32 v46, s13, v71
	v_add_u32_e32 v48, s10, v72
	v_add_u32_e32 v50, s13, v73
	v_add_u32_e32 v52, s10, v74
	v_add_u32_e32 v54, s13, v75
	v_add_u32_e32 v56, s10, v76
	v_add_u32_e32 v58, s13, v77
	v_add_u32_e32 v60, s10, v78
	v_add_u32_e32 v62, s13, v79
	v_add_u32_e32 v66, s10, v80
	v_ashrrev_i32_e32 v35, 31, v34
	v_lshlrev_b64 v[36:37], 12, v[36:37]
	v_ashrrev_i32_e32 v41, 31, v40
	v_ashrrev_i32_e32 v39, 31, v38
	v_ashrrev_i32_e32 v45, 31, v44
	v_ashrrev_i32_e32 v43, 31, v42
	v_ashrrev_i32_e32 v49, 31, v48
	v_ashrrev_i32_e32 v47, 31, v46
	v_ashrrev_i32_e32 v53, 31, v52
	v_ashrrev_i32_e32 v51, 31, v50
	v_ashrrev_i32_e32 v57, 31, v56
	v_ashrrev_i32_e32 v55, 31, v54
	v_ashrrev_i32_e32 v61, 31, v60
	v_ashrrev_i32_e32 v59, 31, v58
	v_ashrrev_i32_e32 v67, 31, v66
	v_ashrrev_i32_e32 v63, 31, v62
	v_lshlrev_b64 v[34:35], 12, v[34:35]
	v_lshl_add_u64 v[36:37], v[28:29], 0, v[36:37]
	v_lshlrev_b64 v[38:39], 12, v[38:39]
	v_lshlrev_b64 v[40:41], 12, v[40:41]
	v_lshlrev_b64 v[42:43], 12, v[42:43]
	v_lshlrev_b64 v[44:45], 12, v[44:45]
	v_lshlrev_b64 v[46:47], 12, v[46:47]
	v_lshlrev_b64 v[48:49], 12, v[48:49]
	v_lshlrev_b64 v[50:51], 12, v[50:51]
	v_lshlrev_b64 v[52:53], 12, v[52:53]
	v_lshlrev_b64 v[54:55], 12, v[54:55]
	v_lshlrev_b64 v[56:57], 12, v[56:57]
	v_lshlrev_b64 v[58:59], 12, v[58:59]
	v_lshlrev_b64 v[60:61], 12, v[60:61]
	v_lshlrev_b64 v[62:63], 12, v[62:63]
	v_lshlrev_b64 v[66:67], 12, v[66:67]
	v_lshl_add_u64 v[34:35], v[28:29], 0, v[34:35]
	v_lshl_add_u64 v[40:41], v[28:29], 0, v[40:41]
	v_lshl_add_u64 v[38:39], v[28:29], 0, v[38:39]
	v_lshl_add_u64 v[44:45], v[28:29], 0, v[44:45]
	v_lshl_add_u64 v[42:43], v[28:29], 0, v[42:43]
	v_lshl_add_u64 v[48:49], v[28:29], 0, v[48:49]
	v_lshl_add_u64 v[46:47], v[28:29], 0, v[46:47]
	v_lshl_add_u64 v[52:53], v[28:29], 0, v[52:53]
	v_lshl_add_u64 v[50:51], v[28:29], 0, v[50:51]
	v_lshl_add_u64 v[56:57], v[28:29], 0, v[56:57]
	v_lshl_add_u64 v[54:55], v[28:29], 0, v[54:55]
	v_lshl_add_u64 v[60:61], v[28:29], 0, v[60:61]
	v_lshl_add_u64 v[58:59], v[28:29], 0, v[58:59]
	v_lshl_add_u64 v[66:67], v[28:29], 0, v[66:67]
	v_lshl_add_u64 v[62:63], v[28:29], 0, v[62:63]
	global_load_dword v81, v[36:37], off
	global_load_dword v82, v[34:35], off
	global_load_dword v83, v[40:41], off
	global_load_dword v84, v[38:39], off
	global_load_dword v85, v[44:45], off
	global_load_dword v86, v[42:43], off
	global_load_dword v87, v[48:49], off
	global_load_dword v88, v[46:47], off
	global_load_dword v89, v[52:53], off
	global_load_dword v90, v[50:51], off
	global_load_dword v91, v[56:57], off
	global_load_dword v92, v[54:55], off
	global_load_dword v93, v[60:61], off
	global_load_dword v94, v[58:59], off
	global_load_dword v95, v[66:67], off
	global_load_dword v96, v[62:63], off
	s_add_i32 s19, s19, 16
	s_add_i32 s11, s11, 16
	s_add_i32 s20, s20, -16
	v_mad_u64_u32 v[34:35], s[38:39], v33, s3, v[24:25]
	s_cmp_lg_u32 s20, 0
	v_mad_u64_u32 v[36:37], s[38:39], v27, s3, v[24:25]
	v_mad_u64_u32 v[38:39], s[38:39], v68, s3, v[24:25]
	v_mad_u64_u32 v[40:41], s[38:39], v64, s3, v[24:25]
	v_mad_u64_u32 v[42:43], s[38:39], v70, s3, v[24:25]
	v_mad_u64_u32 v[44:45], s[38:39], v69, s3, v[24:25]
	v_mad_u64_u32 v[46:47], s[38:39], v72, s3, v[24:25]
	v_mad_u64_u32 v[48:49], s[38:39], v71, s3, v[24:25]
	v_mad_u64_u32 v[50:51], s[38:39], v74, s3, v[24:25]
	v_mad_u64_u32 v[52:53], s[38:39], v73, s3, v[24:25]
	v_mad_u64_u32 v[54:55], s[38:39], v76, s3, v[24:25]
	v_mad_u64_u32 v[56:57], s[38:39], v75, s3, v[24:25]
	v_mad_u64_u32 v[58:59], s[38:39], v78, s3, v[24:25]
	v_mad_u64_u32 v[60:61], s[38:39], v77, s3, v[24:25]
	v_mad_u64_u32 v[62:63], s[38:39], v80, s3, v[24:25]
	v_mad_u64_u32 v[66:67], s[38:39], v79, s3, v[24:25]
	s_lshl_b32 s21, s11, 1
	s_lshl_b32 s36, s19, 1
	v_or_b32_e32 v183, s21, v1
	v_or_b32_e32 v117, s36, v2
	s_add_i32 s38, s21, 4
	s_add_i32 s39, s36, 4
	s_add_i32 s40, s21, 8
	s_add_i32 s41, s36, 8
	s_add_i32 s42, s21, 12
	s_add_i32 s43, s36, 12
	s_add_i32 s44, s21, 16
	s_add_i32 s45, s36, 16
	s_add_i32 s46, s21, 20
	s_add_i32 s47, s36, 20
	s_add_i32 s48, s21, 24
	s_add_i32 s49, s36, 24
	s_add_i32 s21, s21, 28
	s_add_i32 s36, s36, 28
	v_add_u32_e32 v120, s10, v117
	v_or_b32_e32 v148, s38, v1
	v_or_b32_e32 v152, s39, v2
	v_or_b32_e32 v153, s40, v1
	v_or_b32_e32 v154, s41, v2
	v_or_b32_e32 v155, s42, v1
	v_or_b32_e32 v156, s43, v2
	v_or_b32_e32 v157, s44, v1
	v_or_b32_e32 v158, s45, v2
	v_or_b32_e32 v159, s46, v1
	v_or_b32_e32 v160, s47, v2
	v_or_b32_e32 v161, s48, v1
	v_or_b32_e32 v162, s49, v2
	v_or_b32_e32 v163, s21, v1
	v_or_b32_e32 v164, s36, v2
	v_add_u32_e32 v118, s13, v183
	v_ashrrev_i32_e32 v121, 31, v120
; __device__ __forceinline__ void wave_lds_fence() { asm volatile("s_waitcnt lgkmcnt(0)" ::: "memory"); __builtin_amdgcn_wave_barrier(); }
; __device__ __forceinline__ void tr_tile(const float* W, int N, int k0, int n0, bf16_t* WT, int ldt, int drow0, float* scr, int lane) {
;     ...
;     for (int i = 0; i < 32; ++i) { const int kk = 2 * i + (lane >> 5); scr[kk * 33 + (lane & 31)] = W[(size_t)(k0 + kk) * N + n0 + (lane & 31)]; }
;     wave_lds_fence();
	v_add_u32_e32 v122, s13, v148
	v_add_u32_e32 v124, s10, v152
	v_add_u32_e32 v126, s13, v153
	v_add_u32_e32 v128, s10, v154
	v_add_u32_e32 v130, s13, v155
	v_add_u32_e32 v132, s10, v156
	v_add_u32_e32 v134, s13, v157
	v_add_u32_e32 v136, s10, v158
	v_add_u32_e32 v138, s13, v159
	v_add_u32_e32 v140, s10, v160
	v_add_u32_e32 v142, s13, v161
	v_add_u32_e32 v144, s10, v162
	v_add_u32_e32 v146, s13, v163
	v_add_u32_e32 v150, s10, v164
	v_ashrrev_i32_e32 v119, 31, v118
	v_lshlrev_b64 v[120:121], 12, v[120:121]
	v_ashrrev_i32_e32 v125, 31, v124
	v_ashrrev_i32_e32 v123, 31, v122
	v_ashrrev_i32_e32 v129, 31, v128
	v_ashrrev_i32_e32 v127, 31, v126
	v_ashrrev_i32_e32 v133, 31, v132
	v_ashrrev_i32_e32 v131, 31, v130
	v_ashrrev_i32_e32 v137, 31, v136
	v_ashrrev_i32_e32 v135, 31, v134
	v_ashrrev_i32_e32 v141, 31, v140
	v_ashrrev_i32_e32 v139, 31, v138
	v_ashrrev_i32_e32 v145, 31, v144
	v_ashrrev_i32_e32 v143, 31, v142
	v_ashrrev_i32_e32 v151, 31, v150
	v_ashrrev_i32_e32 v147, 31, v146
	v_lshlrev_b64 v[118:119], 12, v[118:119]
	v_lshl_add_u64 v[120:121], v[28:29], 0, v[120:121]
	v_lshlrev_b64 v[122:123], 12, v[122:123]
	v_lshlrev_b64 v[124:125], 12, v[124:125]
	v_lshlrev_b64 v[126:127], 12, v[126:127]
	v_lshlrev_b64 v[128:129], 12, v[128:129]
	v_lshlrev_b64 v[130:131], 12, v[130:131]
	v_lshlrev_b64 v[132:133], 12, v[132:133]
	v_lshlrev_b64 v[134:135], 12, v[134:135]
	v_lshlrev_b64 v[136:137], 12, v[136:137]
	v_lshlrev_b64 v[138:139], 12, v[138:139]
	v_lshlrev_b64 v[140:141], 12, v[140:141]
	v_lshlrev_b64 v[142:143], 12, v[142:143]
	v_lshlrev_b64 v[144:145], 12, v[144:145]
	v_lshlrev_b64 v[146:147], 12, v[146:147]
	v_lshlrev_b64 v[150:151], 12, v[150:151]
	v_lshl_add_u64 v[118:119], v[28:29], 0, v[118:119]
	v_lshl_add_u64 v[124:125], v[28:29], 0, v[124:125]
	v_lshl_add_u64 v[122:123], v[28:29], 0, v[122:123]
	v_lshl_add_u64 v[128:129], v[28:29], 0, v[128:129]
	v_lshl_add_u64 v[126:127], v[28:29], 0, v[126:127]
	v_lshl_add_u64 v[132:133], v[28:29], 0, v[132:133]
	v_lshl_add_u64 v[130:131], v[28:29], 0, v[130:131]
	v_lshl_add_u64 v[136:137], v[28:29], 0, v[136:137]
	v_lshl_add_u64 v[134:135], v[28:29], 0, v[134:135]
	v_lshl_add_u64 v[140:141], v[28:29], 0, v[140:141]
	v_lshl_add_u64 v[138:139], v[28:29], 0, v[138:139]
	v_lshl_add_u64 v[144:145], v[28:29], 0, v[144:145]
	v_lshl_add_u64 v[142:143], v[28:29], 0, v[142:143]
	v_lshl_add_u64 v[150:151], v[28:29], 0, v[150:151]
	v_lshl_add_u64 v[146:147], v[28:29], 0, v[146:147]
	global_load_dword v165, v[120:121], off
	global_load_dword v166, v[118:119], off
	global_load_dword v167, v[124:125], off
	global_load_dword v168, v[122:123], off
	global_load_dword v169, v[128:129], off
	global_load_dword v170, v[126:127], off
	global_load_dword v171, v[132:133], off
	global_load_dword v172, v[130:131], off
	global_load_dword v173, v[136:137], off
	global_load_dword v174, v[134:135], off
	global_load_dword v175, v[140:141], off
	global_load_dword v176, v[138:139], off
	global_load_dword v177, v[144:145], off
	global_load_dword v178, v[142:143], off
	global_load_dword v179, v[150:151], off
	global_load_dword v180, v[146:147], off
	s_add_i32 s19, s19, 16
	s_add_i32 s11, s11, 16
	s_add_i32 s20, s20, -16
	v_mad_u64_u32 v[118:119], s[38:39], v117, s3, v[24:25]
	s_cmp_lg_u32 s20, 0
	v_mad_u64_u32 v[120:121], s[38:39], v183, s3, v[24:25]
	v_mad_u64_u32 v[122:123], s[38:39], v152, s3, v[24:25]
	v_mad_u64_u32 v[124:125], s[38:39], v148, s3, v[24:25]
	v_mad_u64_u32 v[126:127], s[38:39], v154, s3, v[24:25]
	v_mad_u64_u32 v[128:129], s[38:39], v153, s3, v[24:25]
	v_mad_u64_u32 v[130:131], s[38:39], v156, s3, v[24:25]
	v_mad_u64_u32 v[132:133], s[38:39], v155, s3, v[24:25]
	v_mad_u64_u32 v[134:135], s[38:39], v158, s3, v[24:25]
	v_mad_u64_u32 v[136:137], s[38:39], v157, s3, v[24:25]
	v_mad_u64_u32 v[138:139], s[38:39], v160, s3, v[24:25]
	v_mad_u64_u32 v[140:141], s[38:39], v159, s3, v[24:25]
	v_mad_u64_u32 v[142:143], s[38:39], v162, s3, v[24:25]
	v_mad_u64_u32 v[144:145], s[38:39], v161, s3, v[24:25]
	v_mad_u64_u32 v[146:147], s[38:39], v164, s3, v[24:25]
	v_mad_u64_u32 v[150:151], s[38:39], v163, s3, v[24:25]
	s_waitcnt vmcnt(31)
	ds_write_b32 v34, v81
	s_waitcnt vmcnt(30)
	ds_write_b32 v36, v82
	s_waitcnt vmcnt(29)
	ds_write_b32 v38, v83
	s_waitcnt vmcnt(28)
	ds_write_b32 v40, v84
	s_waitcnt vmcnt(27)
	ds_write_b32 v42, v85
	s_waitcnt vmcnt(26)
	ds_write_b32 v44, v86
	s_waitcnt vmcnt(25)
	ds_write_b32 v46, v87
	s_waitcnt vmcnt(24)
	ds_write_b32 v48, v88
	s_waitcnt vmcnt(23)
	ds_write_b32 v50, v89
	s_waitcnt vmcnt(22)
	ds_write_b32 v52, v90
	s_waitcnt vmcnt(21)
	ds_write_b32 v54, v91
	s_waitcnt vmcnt(20)
	ds_write_b32 v56, v92
	s_waitcnt vmcnt(19)
	ds_write_b32 v58, v93
	s_waitcnt vmcnt(18)
	ds_write_b32 v60, v94
	s_waitcnt vmcnt(17)
	ds_write_b32 v62, v95
	s_waitcnt vmcnt(16)
	ds_write_b32 v66, v96
	s_waitcnt vmcnt(15)
	ds_write_b32 v118, v165
	s_waitcnt vmcnt(14)
	ds_write_b32 v120, v166
	s_waitcnt vmcnt(13)
	ds_write_b32 v122, v167
	s_waitcnt vmcnt(12)
	ds_write_b32 v124, v168
	s_waitcnt vmcnt(11)
	ds_write_b32 v126, v169
	s_waitcnt vmcnt(10)
	ds_write_b32 v128, v170
	s_waitcnt vmcnt(9)
	ds_write_b32 v130, v171
	s_waitcnt vmcnt(8)
	ds_write_b32 v132, v172
	s_waitcnt vmcnt(7)
	ds_write_b32 v134, v173
	s_waitcnt vmcnt(6)
	ds_write_b32 v136, v174
	s_waitcnt vmcnt(5)
	ds_write_b32 v138, v175
	s_waitcnt vmcnt(4)
	ds_write_b32 v140, v176
	s_waitcnt vmcnt(3)
	ds_write_b32 v142, v177
	s_waitcnt vmcnt(2)
	ds_write_b32 v144, v178
	s_waitcnt vmcnt(1)
	ds_write_b32 v146, v179
	s_waitcnt vmcnt(0)
	ds_write_b32 v150, v180
	s_cbranch_scc1 .LBB0_26
; __device__ __forceinline__ unsigned cvt_pk_bf16(float lo, float hi) { f32x2_t v = {lo, hi}; bf2_t r = __builtin_convertvector(v, bf2_t); return __builtin_bit_cast(unsigned, r); }
; __device__ __forceinline__ void tr_tile(const float* W, int N, int k0, int n0, bf16_t* WT, int ldt, int drow0, float* scr, int lane) {
;     ...
;     const int c = lane & 7;
; #pragma unroll
;     for (int j = 0; j < 4; ++j) { const int n = (lane >> 3) + 8 * j; const float* s = scr + (8 * c) * 33 + n;
;         u32x4 o; o.x = cvt_pk_bf16(s[0 * 33], s[1 * 33]); o.y = cvt_pk_bf16(s[2 * 33], s[3 * 33]); o.z = cvt_pk_bf16(s[4 * 33], s[5 * 33]); o.w = cvt_pk_bf16(s[6 * 33], s[7 * 33]);
;         *(u32x4*)(WT + (size_t)(drow0 + n) * ldt + k0 + 8 * c) = o; }
	s_waitcnt lgkmcnt(0)
	ds_read2_b32 v[28:29], v25 offset0:33 offset1:41
	ds_read2_b32 v[38:39], v25 offset1:8
	ds_read2_b32 v[40:41], v25 offset0:66 offset1:74
	ds_read2_b32 v[42:43], v25 offset0:99 offset1:107
	ds_read2_b32 v[44:45], v25 offset0:132 offset1:140
	ds_read2_b32 v[46:47], v25 offset0:165 offset1:173
	ds_read2_b32 v[48:49], v25 offset0:198 offset1:206
	ds_read2_b32 v[50:51], v25 offset0:231 offset1:239
	s_mov_b32 s11, s37
	v_or_b32_e32 v27, s12, v5
	v_lshl_add_u64 v[52:53], s[10:11], 1, v[14:15]
	v_lshlrev_b32_e32 v64, 11, v27
	s_waitcnt lgkmcnt(6)
	v_cvt_pk_bf16_f32 v34, v38, v28
	s_waitcnt lgkmcnt(4)
	v_cvt_pk_bf16_f32 v35, v40, v42
	s_waitcnt lgkmcnt(2)
	v_cvt_pk_bf16_f32 v36, v44, v46
	s_waitcnt lgkmcnt(0)
	v_cvt_pk_bf16_f32 v37, v48, v50
	v_lshl_add_u64 v[54:55], v[52:53], 0, v[64:65]
	global_store_dwordx4 v[54:55], v[34:37], off
	v_or_b32_e32 v27, s12, v30
	v_lshlrev_b32_e32 v64, 11, v27
	v_cvt_pk_bf16_f32 v34, v39, v29
	v_cvt_pk_bf16_f32 v35, v41, v43
	v_cvt_pk_bf16_f32 v36, v45, v47
	v_cvt_pk_bf16_f32 v37, v49, v51
	ds_read2_b32 v[38:39], v25 offset0:49 offset1:57
	ds_read2_b32 v[40:41], v25 offset0:16 offset1:24
	ds_read2_b32 v[42:43], v25 offset0:82 offset1:90
	ds_read2_b32 v[44:45], v25 offset0:115 offset1:123
	ds_read2_b32 v[46:47], v25 offset0:148 offset1:156
	ds_read2_b32 v[48:49], v25 offset0:181 offset1:189
	ds_read2_b32 v[50:51], v25 offset0:214 offset1:222
	ds_read2_b32 v[54:55], v25 offset0:247 offset1:255
	v_or_b32_e32 v27, s12, v31
	v_lshl_add_u64 v[28:29], v[52:53], 0, v[64:65]
	v_lshlrev_b32_e32 v64, 11, v27
	v_or_b32_e32 v27, s12, v32
	global_store_dwordx4 v[28:29], v[34:37], off
	v_lshl_add_u64 v[28:29], v[52:53], 0, v[64:65]
	v_lshlrev_b32_e32 v64, 11, v27
	s_waitcnt lgkmcnt(6)
	v_cvt_pk_bf16_f32 v34, v40, v38
	s_waitcnt lgkmcnt(4)
	v_cvt_pk_bf16_f32 v35, v42, v44
	s_waitcnt lgkmcnt(2)
	v_cvt_pk_bf16_f32 v36, v46, v48
	s_waitcnt lgkmcnt(0)
	v_cvt_pk_bf16_f32 v37, v50, v54
	global_store_dwordx4 v[28:29], v[34:37], off
	v_lshl_add_u64 v[28:29], v[52:53], 0, v[64:65]
	v_readlane_b32 s40, v254, 53
	v_cvt_pk_bf16_f32 v34, v41, v39
	v_cvt_pk_bf16_f32 v35, v43, v45
	v_cvt_pk_bf16_f32 v36, v47, v49
	v_cvt_pk_bf16_f32 v37, v51, v55
	global_store_dwordx4 v[28:29], v[34:37], off
	s_waitcnt lgkmcnt(0)
	v_readlane_b32 s41, v254, 54

; __device__ __forceinline__ void wave_lds_fence() { asm volatile("s_waitcnt lgkmcnt(0)" ::: "memory"); __builtin_amdgcn_wave_barrier(); }
; __device__ __forceinline__ void tr_tile(const float* W, int N, int k0, int n0, bf16_t* WT, int ldt, int drow0, float* scr, int lane) {
; #pragma unroll 8
;     for (int i = 0; i < 32; ++i) { const int kk = 2 * i + (lane >> 5); scr[kk * 33 + (lane & 31)] = W[(size_t)(k0 + kk) * N + n0 + (lane & 31)]; }
;     wave_lds_fence();
.LBB0_41:
	s_lshl_b32 s21, s13, 1
	s_lshl_b32 s36, s19, 1
	v_or_b32_e32 v27, s21, v1
	v_or_b32_e32 v33, s36, v2
	s_add_i32 s38, s21, 4
	s_add_i32 s39, s36, 4
	s_add_i32 s40, s21, 8
	s_add_i32 s41, s36, 8
	s_add_i32 s42, s21, 12
	s_add_i32 s43, s36, 12
	s_add_i32 s44, s21, 16
	s_add_i32 s45, s36, 16
	s_add_i32 s46, s21, 20
	s_add_i32 s47, s36, 20
	s_add_i32 s48, s21, 24
	s_add_i32 s49, s36, 24
	s_add_i32 s21, s21, 28
	s_add_i32 s36, s36, 28
	v_add_u32_e32 v34, s12, v33
	v_or_b32_e32 v64, s38, v1
	v_or_b32_e32 v68, s39, v2
	v_or_b32_e32 v69, s40, v1
	v_or_b32_e32 v70, s41, v2
	v_or_b32_e32 v71, s42, v1
	v_or_b32_e32 v72, s43, v2
	v_or_b32_e32 v73, s44, v1
	v_or_b32_e32 v74, s45, v2
	v_or_b32_e32 v75, s46, v1
	v_or_b32_e32 v76, s47, v2
	v_or_b32_e32 v77, s48, v1
	v_or_b32_e32 v78, s49, v2
	v_or_b32_e32 v79, s21, v1
	v_or_b32_e32 v80, s36, v2
	v_add_u32_e32 v36, s11, v27
	v_mad_i64_i32 v[34:35], s[38:39], v34, s33, v[28:29]
	v_add_u32_e32 v40, s11, v64
	v_add_u32_e32 v38, s12, v68
	v_add_u32_e32 v44, s11, v69
	v_add_u32_e32 v42, s12, v70
	v_add_u32_e32 v48, s11, v71
	v_add_u32_e32 v46, s12, v72
	v_add_u32_e32 v52, s11, v73
	v_add_u32_e32 v50, s12, v74
	v_add_u32_e32 v56, s11, v75
	v_add_u32_e32 v54, s12, v76
	v_add_u32_e32 v60, s11, v77
	v_add_u32_e32 v58, s12, v78
	v_add_u32_e32 v66, s11, v79
	v_add_u32_e32 v62, s12, v80
	v_mad_i64_i32 v[36:37], s[38:39], v36, s33, v[28:29]
	v_mad_i64_i32 v[38:39], s[38:39], v38, s33, v[28:29]
	v_mad_i64_i32 v[40:41], s[38:39], v40, s33, v[28:29]
	v_mad_i64_i32 v[42:43], s[38:39], v42, s33, v[28:29]
	v_mad_i64_i32 v[44:45], s[38:39], v44, s33, v[28:29]
	v_mad_i64_i32 v[46:47], s[38:39], v46, s33, v[28:29]
	v_mad_i64_i32 v[48:49], s[38:39], v48, s33, v[28:29]
	v_mad_i64_i32 v[50:51], s[38:39], v50, s33, v[28:29]
	v_mad_i64_i32 v[52:53], s[38:39], v52, s33, v[28:29]
	v_mad_i64_i32 v[54:55], s[38:39], v54, s33, v[28:29]
	v_mad_i64_i32 v[56:57], s[38:39], v56, s33, v[28:29]
	v_mad_i64_i32 v[58:59], s[38:39], v58, s33, v[28:29]
	v_mad_i64_i32 v[60:61], s[38:39], v60, s33, v[28:29]
	v_mad_i64_i32 v[62:63], s[38:39], v62, s33, v[28:29]
	v_mad_i64_i32 v[66:67], s[38:39], v66, s33, v[28:29]
	global_load_dword v81, v[34:35], off
	global_load_dword v82, v[36:37], off
	global_load_dword v83, v[38:39], off
	global_load_dword v84, v[40:41], off
	global_load_dword v85, v[42:43], off
	global_load_dword v86, v[44:45], off
	global_load_dword v87, v[46:47], off
	global_load_dword v88, v[48:49], off
	global_load_dword v89, v[50:51], off
	global_load_dword v90, v[52:53], off
	global_load_dword v91, v[54:55], off
	global_load_dword v92, v[56:57], off
	global_load_dword v93, v[58:59], off
	global_load_dword v94, v[60:61], off
	global_load_dword v95, v[62:63], off
	global_load_dword v96, v[66:67], off
	s_add_i32 s19, s19, 16
	s_add_i32 s13, s13, 16
	s_add_i32 s20, s20, -16
	v_mad_u64_u32 v[34:35], s[38:39], v33, s3, v[24:25]
	s_cmp_lg_u32 s20, 0
	v_mad_u64_u32 v[36:37], s[38:39], v27, s3, v[24:25]
	v_mad_u64_u32 v[38:39], s[38:39], v68, s3, v[24:25]
	v_mad_u64_u32 v[40:41], s[38:39], v64, s3, v[24:25]
	v_mad_u64_u32 v[42:43], s[38:39], v70, s3, v[24:25]
	v_mad_u64_u32 v[44:45], s[38:39], v69, s3, v[24:25]
	v_mad_u64_u32 v[46:47], s[38:39], v72, s3, v[24:25]
	v_mad_u64_u32 v[48:49], s[38:39], v71, s3, v[24:25]
	v_mad_u64_u32 v[50:51], s[38:39], v74, s3, v[24:25]
	v_mad_u64_u32 v[52:53], s[38:39], v73, s3, v[24:25]
	v_mad_u64_u32 v[54:55], s[38:39], v76, s3, v[24:25]
	v_mad_u64_u32 v[56:57], s[38:39], v75, s3, v[24:25]
	v_mad_u64_u32 v[58:59], s[38:39], v78, s3, v[24:25]
	v_mad_u64_u32 v[60:61], s[38:39], v77, s3, v[24:25]
	v_mad_u64_u32 v[62:63], s[38:39], v80, s3, v[24:25]
	v_mad_u64_u32 v[66:67], s[38:39], v79, s3, v[24:25]
	s_lshl_b32 s21, s13, 1
	s_lshl_b32 s36, s19, 1
	v_or_b32_e32 v183, s21, v1
	v_or_b32_e32 v117, s36, v2
	s_add_i32 s38, s21, 4
	s_add_i32 s39, s36, 4
	s_add_i32 s40, s21, 8
	s_add_i32 s41, s36, 8
	s_add_i32 s42, s21, 12
	s_add_i32 s43, s36, 12
	s_add_i32 s44, s21, 16
	s_add_i32 s45, s36, 16
	s_add_i32 s46, s21, 20
	s_add_i32 s47, s36, 20
	s_add_i32 s48, s21, 24
	s_add_i32 s49, s36, 24
	s_add_i32 s21, s21, 28
	s_add_i32 s36, s36, 28
	v_add_u32_e32 v118, s12, v117
	v_or_b32_e32 v148, s38, v1
	v_or_b32_e32 v152, s39, v2
	v_or_b32_e32 v153, s40, v1
	v_or_b32_e32 v154, s41, v2
	v_or_b32_e32 v155, s42, v1
	v_or_b32_e32 v156, s43, v2
	v_or_b32_e32 v157, s44, v1
	v_or_b32_e32 v158, s45, v2
	v_or_b32_e32 v159, s46, v1
	v_or_b32_e32 v160, s47, v2
	v_or_b32_e32 v161, s48, v1
	v_or_b32_e32 v162, s49, v2
	v_or_b32_e32 v163, s21, v1
	v_or_b32_e32 v164, s36, v2
	v_add_u32_e32 v120, s11, v183
	v_mad_i64_i32 v[118:119], s[38:39], v118, s33, v[28:29]
	v_add_u32_e32 v124, s11, v148
	v_add_u32_e32 v122, s12, v152
	v_add_u32_e32 v128, s11, v153
	v_add_u32_e32 v126, s12, v154
	v_add_u32_e32 v132, s11, v155
	v_add_u32_e32 v130, s12, v156
	v_add_u32_e32 v136, s11, v157
	v_add_u32_e32 v134, s12, v158
	v_add_u32_e32 v140, s11, v159
	v_add_u32_e32 v138, s12, v160
	v_add_u32_e32 v144, s11, v161
	v_add_u32_e32 v142, s12, v162
	v_add_u32_e32 v150, s11, v163
	v_add_u32_e32 v146, s12, v164
	v_mad_i64_i32 v[120:121], s[38:39], v120, s33, v[28:29]
	v_mad_i64_i32 v[122:123], s[38:39], v122, s33, v[28:29]
	v_mad_i64_i32 v[124:125], s[38:39], v124, s33, v[28:29]
	v_mad_i64_i32 v[126:127], s[38:39], v126, s33, v[28:29]
	v_mad_i64_i32 v[128:129], s[38:39], v128, s33, v[28:29]
	v_mad_i64_i32 v[130:131], s[38:39], v130, s33, v[28:29]
	v_mad_i64_i32 v[132:133], s[38:39], v132, s33, v[28:29]
	v_mad_i64_i32 v[134:135], s[38:39], v134, s33, v[28:29]
	v_mad_i64_i32 v[136:137], s[38:39], v136, s33, v[28:29]
	v_mad_i64_i32 v[138:139], s[38:39], v138, s33, v[28:29]
; __device__ __forceinline__ unsigned cvt_pk_bf16(float lo, float hi) { f32x2_t v = {lo, hi}; bf2_t r = __builtin_convertvector(v, bf2_t); return __builtin_bit_cast(unsigned, r); }
; __device__ __forceinline__ void wave_lds_fence() { asm volatile("s_waitcnt lgkmcnt(0)" ::: "memory"); __builtin_amdgcn_wave_barrier(); }
; __device__ __forceinline__ void tr_tile(const float* W, int N, int k0, int n0, bf16_t* WT, int ldt, int drow0, float* scr, int lane) {
;     ...
;     for (int i = 0; i < 32; ++i) { const int kk = 2 * i + (lane >> 5); scr[kk * 33 + (lane & 31)] = W[(size_t)(k0 + kk) * N + n0 + (lane & 31)]; }
;     wave_lds_fence();
;     const int c = lane & 7;
; #pragma unroll
;     for (int j = 0; j < 4; ++j) { const int n = (lane >> 3) + 8 * j; const float* s = scr + (8 * c) * 33 + n;
;         u32x4 o; o.x = cvt_pk_bf16(s[0 * 33], s[1 * 33]); o.y = cvt_pk_bf16(s[2 * 33], s[3 * 33]); o.z = cvt_pk_bf16(s[4 * 33], s[5 * 33]); o.w = cvt_pk_bf16(s[6 * 33], s[7 * 33]);
;         *(u32x4*)(WT + (size_t)(drow0 + n) * ldt + k0 + 8 * c) = o; }
	v_mad_i64_i32 v[140:141], s[38:39], v140, s33, v[28:29]
	v_mad_i64_i32 v[142:143], s[38:39], v142, s33, v[28:29]
	v_mad_i64_i32 v[144:145], s[38:39], v144, s33, v[28:29]
	v_mad_i64_i32 v[146:147], s[38:39], v146, s33, v[28:29]
	v_mad_i64_i32 v[150:151], s[38:39], v150, s33, v[28:29]
	global_load_dword v165, v[118:119], off
	global_load_dword v166, v[120:121], off
	global_load_dword v167, v[122:123], off
	global_load_dword v168, v[124:125], off
	global_load_dword v169, v[126:127], off
	global_load_dword v170, v[128:129], off
	global_load_dword v171, v[130:131], off
	global_load_dword v172, v[132:133], off
	global_load_dword v173, v[134:135], off
	global_load_dword v174, v[136:137], off
	global_load_dword v175, v[138:139], off
	global_load_dword v176, v[140:141], off
	global_load_dword v177, v[142:143], off
	global_load_dword v178, v[144:145], off
	global_load_dword v179, v[146:147], off
	global_load_dword v180, v[150:151], off
	s_add_i32 s19, s19, 16
	s_add_i32 s13, s13, 16
	s_add_i32 s20, s20, -16
	v_mad_u64_u32 v[118:119], s[38:39], v117, s3, v[24:25]
	s_cmp_lg_u32 s20, 0
	v_mad_u64_u32 v[120:121], s[38:39], v183, s3, v[24:25]
	v_mad_u64_u32 v[122:123], s[38:39], v152, s3, v[24:25]
	v_mad_u64_u32 v[124:125], s[38:39], v148, s3, v[24:25]
	v_mad_u64_u32 v[126:127], s[38:39], v154, s3, v[24:25]
	v_mad_u64_u32 v[128:129], s[38:39], v153, s3, v[24:25]
	v_mad_u64_u32 v[130:131], s[38:39], v156, s3, v[24:25]
	v_mad_u64_u32 v[132:133], s[38:39], v155, s3, v[24:25]
	v_mad_u64_u32 v[134:135], s[38:39], v158, s3, v[24:25]
	v_mad_u64_u32 v[136:137], s[38:39], v157, s3, v[24:25]
	v_mad_u64_u32 v[138:139], s[38:39], v160, s3, v[24:25]
	v_mad_u64_u32 v[140:141], s[38:39], v159, s3, v[24:25]
	v_mad_u64_u32 v[142:143], s[38:39], v162, s3, v[24:25]
	v_mad_u64_u32 v[144:145], s[38:39], v161, s3, v[24:25]
	v_mad_u64_u32 v[146:147], s[38:39], v164, s3, v[24:25]
	v_mad_u64_u32 v[150:151], s[38:39], v163, s3, v[24:25]
	s_waitcnt vmcnt(31)
	ds_write_b32 v34, v81
	s_waitcnt vmcnt(30)
	ds_write_b32 v36, v82
	s_waitcnt vmcnt(29)
	ds_write_b32 v38, v83
	s_waitcnt vmcnt(28)
	ds_write_b32 v40, v84
	s_waitcnt vmcnt(27)
	ds_write_b32 v42, v85
	s_waitcnt vmcnt(26)
	ds_write_b32 v44, v86
	s_waitcnt vmcnt(25)
	ds_write_b32 v46, v87
	s_waitcnt vmcnt(24)
	ds_write_b32 v48, v88
	s_waitcnt vmcnt(23)
	ds_write_b32 v50, v89
	s_waitcnt vmcnt(22)
	ds_write_b32 v52, v90
	s_waitcnt vmcnt(21)
	ds_write_b32 v54, v91
	s_waitcnt vmcnt(20)
	ds_write_b32 v56, v92
	s_waitcnt vmcnt(19)
	ds_write_b32 v58, v93
	s_waitcnt vmcnt(18)
	ds_write_b32 v60, v94
	s_waitcnt vmcnt(17)
	ds_write_b32 v62, v95
	s_waitcnt vmcnt(16)
	ds_write_b32 v66, v96
	s_waitcnt vmcnt(15)
	ds_write_b32 v118, v165
	s_waitcnt vmcnt(14)
	ds_write_b32 v120, v166
	s_waitcnt vmcnt(13)
	ds_write_b32 v122, v167
	s_waitcnt vmcnt(12)
	ds_write_b32 v124, v168
	s_waitcnt vmcnt(11)
	ds_write_b32 v126, v169
	s_waitcnt vmcnt(10)
	ds_write_b32 v128, v170
	s_waitcnt vmcnt(9)
	ds_write_b32 v130, v171
	s_waitcnt vmcnt(8)
	ds_write_b32 v132, v172
	s_waitcnt vmcnt(7)
	ds_write_b32 v134, v173
	s_waitcnt vmcnt(6)
	ds_write_b32 v136, v174
	s_waitcnt vmcnt(5)
	ds_write_b32 v138, v175
	s_waitcnt vmcnt(4)
	ds_write_b32 v140, v176
	s_waitcnt vmcnt(3)
	ds_write_b32 v142, v177
	s_waitcnt vmcnt(2)
	ds_write_b32 v144, v178
	s_waitcnt vmcnt(1)
	ds_write_b32 v146, v179
	s_waitcnt vmcnt(0)
	ds_write_b32 v150, v180
	s_cbranch_scc1 .LBB0_41
	s_waitcnt lgkmcnt(0)
	ds_read2_b32 v[28:29], v25 offset0:33 offset1:41
	ds_read2_b32 v[38:39], v25 offset1:8
	ds_read2_b32 v[40:41], v25 offset0:66 offset1:74
	ds_read2_b32 v[42:43], v25 offset0:99 offset1:107
	ds_read2_b32 v[44:45], v25 offset0:132 offset1:140
	ds_read2_b32 v[46:47], v25 offset0:165 offset1:173
	ds_read2_b32 v[48:49], v25 offset0:198 offset1:206
	ds_read2_b32 v[50:51], v25 offset0:231 offset1:239
	v_or_b32_e32 v54, s10, v5
	s_ashr_i32 s13, s12, 31
	v_ashrrev_i32_e32 v55, 31, v54
	v_lshl_add_u64 v[52:53], s[12:13], 1, v[22:23]
	v_lshlrev_b64 v[54:55], 11, v[54:55]
	s_waitcnt lgkmcnt(6)
	v_cvt_pk_bf16_f32 v34, v38, v28
	s_waitcnt lgkmcnt(4)
	v_cvt_pk_bf16_f32 v35, v40, v42
	s_waitcnt lgkmcnt(2)
	v_cvt_pk_bf16_f32 v36, v44, v46
	s_waitcnt lgkmcnt(0)
	v_cvt_pk_bf16_f32 v37, v48, v50
	v_lshl_add_u64 v[54:55], v[52:53], 0, v[54:55]
	v_or_b32_e32 v28, s10, v30
	global_store_dwordx4 v[54:55], v[34:37], off
	v_readlane_b32 s40, v254, 53
	v_readlane_b32 s41, v254, 54
	v_cvt_pk_bf16_f32 v34, v39, v29
	v_ashrrev_i32_e32 v29, 31, v28
	v_cvt_pk_bf16_f32 v35, v41, v43
	v_cvt_pk_bf16_f32 v36, v45, v47
	v_cvt_pk_bf16_f32 v37, v49, v51
	v_lshlrev_b64 v[28:29], 11, v[28:29]
	ds_read2_b32 v[38:39], v25 offset0:49 offset1:57
	ds_read2_b32 v[40:41], v25 offset0:16 offset1:24
	ds_read2_b32 v[42:43], v25 offset0:82 offset1:90
	ds_read2_b32 v[44:45], v25 offset0:115 offset1:123
	ds_read2_b32 v[46:47], v25 offset0:148 offset1:156
	ds_read2_b32 v[48:49], v25 offset0:181 offset1:189
	ds_read2_b32 v[50:51], v25 offset0:214 offset1:222
	ds_read2_b32 v[54:55], v25 offset0:247 offset1:255
	v_lshl_add_u64 v[28:29], v[52:53], 0, v[28:29]
	global_store_dwordx4 v[28:29], v[34:37], off
	v_or_b32_e32 v28, s10, v31
	v_ashrrev_i32_e32 v29, 31, v28
	v_lshlrev_b64 v[28:29], 11, v[28:29]
	s_waitcnt lgkmcnt(6)
	v_cvt_pk_bf16_f32 v34, v40, v38
	s_waitcnt lgkmcnt(4)
	v_cvt_pk_bf16_f32 v35, v42, v44
	s_waitcnt lgkmcnt(2)
	v_cvt_pk_bf16_f32 v36, v46, v48
	s_waitcnt lgkmcnt(0)
	v_cvt_pk_bf16_f32 v37, v50, v54
	v_lshl_add_u64 v[28:29], v[52:53], 0, v[28:29]
	global_store_dwordx4 v[28:29], v[34:37], off
	v_or_b32_e32 v28, s10, v32
	v_ashrrev_i32_e32 v29, 31, v28
	v_lshlrev_b64 v[28:29], 11, v[28:29]
	v_cvt_pk_bf16_f32 v34, v41, v39
	v_cvt_pk_bf16_f32 v35, v43, v45
	v_cvt_pk_bf16_f32 v36, v47, v49
	v_cvt_pk_bf16_f32 v37, v51, v55
	v_lshl_add_u64 v[28:29], v[52:53], 0, v[28:29]
	global_store_dwordx4 v[28:29], v[34:37], off
	s_waitcnt lgkmcnt(0)
	s_branch .LBB0_10
